# adds: seam P0-P1 uses the XCD-hierarchical barrier instead of cg grid sync; P8 sample-row split-K partial loads 16 in flight; P10 row-ssq exchange 8 loads together
# speedup vs baseline: 1.0329x; 1.0200x over previous
; __device__ __forceinline__ unsigned xb_ld(unsigned* p)              { return __hip_atomic_load(p, __ATOMIC_RELAXED, __HIP_MEMORY_SCOPE_AGENT); }
; __device__ __forceinline__ unsigned xb_add(unsigned* p, unsigned v) { return __hip_atomic_fetch_add(p, v, __ATOMIC_RELAXED, __HIP_MEMORY_SCOPE_AGENT); }
; __device__ __forceinline__ void xcd_barrier_complete(unsigned* bar, unsigned x, unsigned& nloc, unsigned& nx) {
;     const unsigned G = gridDim.x * gridDim.y * gridDim.z;
;     unsigned sum, cnt, mine, sp = 0u;
;     for (;;) {
;         sum = 0u; cnt = 0u; mine = 0u;
; #pragma unroll
;         for (unsigned j = 0; j < 16; ++j) { const unsigned c = xb_ld(&bar[XB_XCNT(j)]); sum += c; cnt += (c > 0u) ? 1u : 0u; mine = (j == x) ? c : mine; }
;         if (sum == G) break;
;         __builtin_amdgcn_s_sleep(1);
;         if ((++sp & 255u) == 0u) { if (xb_ld(&bar[XB_TMO])) break; if (sp > XB_SPIN_CAP) { (void)xb_add(&bar[XB_TMO], 1u); break; } }
;     }
;     nloc = mine > 0u ? mine : 1u; nx = cnt > 0u ? cnt : 1u;
; }
; __device__ __forceinline__ void xcd_barrier(const XcdBarrier& b) {
;     asm volatile("s_waitcnt vmcnt(0)" ::: "memory");
;     __syncthreads();
;     if (threadIdx.x == 0) {
;         unsigned* bar = b.bar;
;         __builtin_amdgcn_s_waitcnt(0);
;         unsigned nloc = b.st[0], nx = b.st[1];
;         if (nloc == 0u) { xcd_barrier_complete(bar, b.x, nloc, nx); b.st[0] = nloc; b.st[1] = nx; }
;         const unsigned old = xb_add(&bar[XB_XSUB(b.x)], 1u);
;         const unsigned gen = old / nloc;
;         if (old + 1u == (gen + 1u) * nloc) {
;             __builtin_amdgcn_fence(__ATOMIC_RELEASE, "agent");
;             asm volatile("s_waitcnt vmcnt(0)" ::: "memory");
;             const unsigned og = xb_add(&bar[XB_TOP], 1u);
;             const unsigned tg = og / nx;
;             if (og + 1u == (tg + 1u) * nx) xb_add(&bar[XB_TOPGEN], 1u);
;             else XB_SPIN(xb_ld(&bar[XB_TOPGEN]) == tg, bar);
;             __builtin_amdgcn_fence(__ATOMIC_ACQUIRE, "agent");
;             xb_add(&bar[XB_XGEN(b.x)], 1u);
;             asm volatile("s_waitcnt vmcnt(0)" ::: "memory");
;         } else {
;             XB_SPIN(xb_ld(&bar[XB_XGEN(b.x)]) == gen, bar);
;             __builtin_amdgcn_fence(__ATOMIC_ACQUIRE, "agent");
;             asm volatile("s_waitcnt vmcnt(0)" ::: "memory");
;         }
;     }
;     __syncthreads();
; }
.LBB0_71:
	s_cmp_gt_i32 s87, 1
	s_cselect_b64 s[2:3], -1, 0
	s_and_b64 s[4:5], s[12:13], s[2:3]
	s_andn2_b64 vcc, exec, s[4:5]
	s_cbranch_vccnz .LBB0_83
	s_waitcnt vmcnt(0)
	s_waitcnt vmcnt(0) lgkmcnt(0)
	s_barrier
	s_mov_b64 s[4:5], exec
	v_readlane_b32 s6, v245, 1
	v_readlane_b32 s7, v245, 2
	s_and_b64 s[6:7], s[4:5], s[6:7]
	s_mov_b64 exec, s[6:7]
	s_cbranch_execz .Lmy_s0_192
	s_add_i32 s6, 0, 0x23ff0
	v_mov_b32_e32 v0, s6
	s_waitcnt vmcnt(0) expcnt(0) lgkmcnt(0)
	ds_read_b32 v2, v0
	s_add_i32 s6, 0, 0x23ff4
	v_mov_b32_e32 v0, s6
	ds_read_b32 v0, v0
	s_waitcnt lgkmcnt(1)
	v_cmp_ne_u32_e32 vcc, 0, v2
	s_cbranch_vccnz .Lmy_s0_160
	s_load_dword s6, s[0:1], 0xe0
	s_mov_b32 s29, 1
	v_mov_b32_e32 v16, 0
	s_waitcnt lgkmcnt(0)
	s_mul_i32 s28, s89, s6
	s_add_u32 s6, s84, 0x1da00300
	s_addc_u32 s7, s85, 0
	s_add_u32 s8, s84, 0x1da00500
	s_addc_u32 s9, s85, 0
	s_add_u32 s10, s84, 0x1da00600
	s_addc_u32 s11, s85, 0
	s_add_u32 s12, s84, 0x1da00700
	s_addc_u32 s13, s85, 0
	s_add_u32 s14, s84, 0x1da00800
	s_addc_u32 s15, s85, 0
	s_add_u32 s16, s84, 0x1da00900
	s_addc_u32 s17, s85, 0
	s_add_u32 s18, s84, 0x1da00a00
	s_addc_u32 s19, s85, 0
	s_add_u32 s20, s84, 0x1da00b00
	s_addc_u32 s21, s85, 0
	s_add_u32 s22, s84, 0x1da00c00
	s_addc_u32 s23, s85, 0
	s_add_u32 s24, s84, 0x1da00d00
	s_addc_u32 s25, s85, 0
	s_add_u32 s26, s84, 0x1da00e00
	s_addc_u32 s27, s85, 0
	s_add_u32 s30, s84, 0x1da00f00
	s_addc_u32 s31, s85, 0
	s_add_u32 s34, s84, 0x1da01000
	s_addc_u32 s35, s85, 0
	s_add_u32 s42, s84, 0x1da01100
	s_addc_u32 s43, s85, 0
	s_add_u32 s44, s84, 0x1da01200
	s_addc_u32 s45, s85, 0
	s_add_u32 s46, s84, 0x1da01300
	s_addc_u32 s47, s85, 0
	s_add_u32 s48, s84, 0x1da01400
	s_mul_i32 s28, s28, s88
	s_addc_u32 s49, s85, 0
	s_branch .Lmy_s0_148

; #define SEAM(k) do { if (IN(k) && IN((k) + 1)) { if ((k) == 0) grid.sync(); else xcd_barrier(xbar); } } while (0)
; __device__ __forceinline__ TileDesc tile_desc(const Frame& F, int t) {
;     unsigned char* ws = F.ws; TileDesc d; int NT, idx; d.kind = 0;
;     if (t < 1536) { d.src = F.in[12]; d.ldn = NMOD; d.K = D; NT = 48; idx = t; d.dst = (bf16_t*)(ws + WS_WADA); }
;     else if (t < 2240) { d.src = F.in[14]; d.ldn = INW; d.K = D; NT = 22; idx = t - 1536; d.dst = (bf16_t*)(ws + WS_WIN); }
;     else if (t < 2496) { d.src = F.in[19]; d.ldn = D; d.K = D; NT = 8; idx = t - 2240; d.dst = (bf16_t*)(ws + WS_WOUT); }
;     else if (t < 3200) { d.src = F.in[20]; d.ldn = DFF; d.K = D; NT = 22; idx = t - 2496; d.dst = (bf16_t*)(ws + WS_WGU); d.kind = 1; }
;     else if (t < 3904) { d.src = F.in[21]; d.ldn = DFF; d.K = D; NT = 22; idx = t - 3200; d.dst = (bf16_t*)(ws + WS_WGU); d.kind = 2; }
;     else { d.src = F.in[22]; d.ldn = D; d.K = DFF; NT = 8; idx = t - 3904; d.dst = (bf16_t*)(ws + WS_WDN); }
; __global__ void __launch_bounds__(512, 2) fwd_mega(Params prm) {
;     ...
;     SEAM(0);
;     if (IN(1)) { { const int cb = F.G > 96 ? 48 : 0;
;           if (F.bid >= cb) convert_tiles(F, 2496, 4608, F.bid - cb, F.G - cb); }
.Lmy_s0_192:
	s_or_b64 exec, exec, s[4:5]
	s_waitcnt lgkmcnt(0)
	s_barrier
.LBB0_83:
	s_cmp_lt_i32 s86, 2
	s_cselect_b64 s[4:5], -1, 0
	s_add_u32 s6, s84, 0x9100000
	s_addc_u32 s7, s85, 0
	s_and_b64 s[14:15], s[4:5], s[2:3]
	v_writelane_b32 v245, s6, 54
	s_andn2_b64 vcc, exec, s[14:15]
	s_nop 0
	v_writelane_b32 v245, s7, 55
	s_cbranch_vccnz .LBB0_143
	s_cmpk_gt_i32 s88, 0x60
	s_waitcnt lgkmcnt(0)
	s_cselect_b32 s16, 48, 0
	s_cmp_lt_i32 s33, s16
	s_cbranch_scc1 .LBB0_115
	s_sub_i32 s8, s33, s16
	s_cmpk_gt_u32 s8, 0x83f
	s_cbranch_scc1 .LBB0_115
	s_cmpk_lt_u32 s8, 0x2c0
	s_mov_b32 s13, 1
	s_cbranch_scc1 .LBB0_90
	s_cmpk_gt_u32 s8, 0x57f
	s_cbranch_scc0 .LBB0_91
	s_load_dwordx16 s[36:51], s[0:1], 0x80
	s_add_i32 s9, s8, 0xfffffa80
	s_waitcnt lgkmcnt(0)
	s_mov_b64 s[4:5], s[48:49]
	s_cbranch_execz .LBB0_92
	s_mov_b64 s[6:7], 0x7a00000
	s_mov_b64 s[2:3], 0x800
	s_movk_i32 s24, 0x1600
	s_mov_b32 s13, 0
	s_mov_b32 s12, 8
	s_branch .LBB0_93

; template <bool GATES>
; __device__ __forceinline__ void norm_mod_phase(const Frame& F, const float* src0, const float* src1, const float* nw, int sh_off, int sc_off, int nparts, float* x1out) {
;     ...
;     for (int r = F.bid * 8 + F.wave; r < MTOT; r += F.G * 8) {
;         const float* xr = r < SP ? src0 + (size_t)r * D : src1 + (size_t)(r - SP) * D;
;         f32x4 xv[8]; float ss = 0.f;
; #pragma unroll
;         for (int i = 0; i < 8; ++i) xv[i] = ((const f32x4*)xr)[i * 64 + F.lane];
;         if (r >= SP) { const float* mr = mod + (size_t)((r - SP) >> 2) * NMOD;
; #pragma unroll
;             for (int i = 0; i < 8; ++i) { const int c4 = i * 64 + F.lane; const f32x4 w = ((const f32x4*)nw)[c4], sc = ((const f32x4*)(mr + sc_off))[c4]; shv[i] = ((const f32x4*)(mr + sh_off))[c4]; av[i] = w * (sc + 1.f); }
.LBB0_966:
	s_add_i32 s4, s2, 0xffffe000
	s_cmpk_lt_i32 s2, 0x2000
	s_cselect_b64 s[10:11], -1, 0
	s_and_b64 vcc, s[10:11], exec
	v_readlane_b32 s36, v245, 37
	s_cselect_b32 s11, s3, 0
	s_cselect_b32 s10, s2, s4
	v_readlane_b32 s38, v245, 39
	v_readlane_b32 s39, v245, 40
	s_cselect_b32 s12, s15, s39
	s_cselect_b32 s13, s14, s38
	s_lshl_b64 s[10:11], s[10:11], 13
	s_add_u32 s10, s13, s10
	s_addc_u32 s11, s12, s11
	v_lshlrev_b32_e32 v128, 4, v160
	global_load_dwordx4 v[56:59], v128, s[10:11]
	global_load_dwordx4 v[52:55], v128, s[10:11] offset:1024
	global_load_dwordx4 v[48:51], v128, s[10:11] offset:2048
	global_load_dwordx4 v[44:47], v128, s[10:11] offset:3072
	global_load_dwordx4 v[40:43], v120, s[10:11]
	global_load_dwordx4 v[36:39], v121, s[10:11]
	global_load_dwordx4 v[32:35], v122, s[10:11]
	global_load_dwordx4 v[60:63], v123, s[10:11]
	v_readlane_b32 s37, v245, 38
	v_readlane_b32 s40, v245, 41
	v_readlane_b32 s41, v245, 42
	v_readlane_b32 s42, v245, 43
	v_readlane_b32 s43, v245, 44
	v_readlane_b32 s44, v245, 45
	v_readlane_b32 s45, v245, 46
	v_readlane_b32 s46, v245, 47
	v_readlane_b32 s47, v245, 48
	v_readlane_b32 s48, v245, 49
	v_readlane_b32 s49, v245, 50
	v_readlane_b32 s50, v245, 51
	v_readlane_b32 s51, v245, 52
	s_cbranch_vccnz .LBB0_965
	s_lshr_b32 s10, s4, 2
	s_mul_hi_u32 s11, s10, 0xc000
	s_mul_i32 s10, s10, 0xc000
	v_readlane_b32 s12, v245, 54
	v_readlane_b32 s13, v245, 55
	s_add_u32 s12, s12, s10
	s_addc_u32 s13, s13, s11
	s_add_u32 s10, s12, 0x8000
	s_addc_u32 s11, s13, 0
	s_add_u32 s12, s12, 0x6000
	s_addc_u32 s13, s13, 0
	global_load_dwordx4 v[4:7], v[72:73], off
	global_load_dwordx4 v[8:11], v128, s[10:11]
	global_load_dwordx4 v[0:3], v128, s[12:13]
	s_waitcnt vmcnt(1)
	v_pk_add_f32 v[10:11], v[10:11], 1.0 op_sel_hi:[1,0]
	v_pk_add_f32 v[8:9], v[8:9], 1.0 op_sel_hi:[1,0]
	v_pk_mul_f32 v[76:77], v[6:7], v[10:11]
	v_pk_mul_f32 v[78:79], v[4:5], v[8:9]
	global_load_dwordx4 v[8:11], v[72:73], off offset:1024
	global_load_dwordx4 v[12:15], v124, s[10:11]
	global_load_dwordx4 v[4:7], v124, s[12:13]
	s_waitcnt vmcnt(1)
	v_pk_add_f32 v[14:15], v[14:15], 1.0 op_sel_hi:[1,0]
	v_pk_add_f32 v[12:13], v[12:13], 1.0 op_sel_hi:[1,0]
	v_pk_mul_f32 v[82:83], v[10:11], v[14:15]
	v_pk_mul_f32 v[84:85], v[8:9], v[12:13]
	global_load_dwordx4 v[12:15], v[72:73], off offset:2048
	global_load_dwordx4 v[16:19], v125, s[10:11]
	global_load_dwordx4 v[8:11], v125, s[12:13]
	s_waitcnt vmcnt(1)
	v_pk_add_f32 v[18:19], v[18:19], 1.0 op_sel_hi:[1,0]
	v_pk_add_f32 v[16:17], v[16:17], 1.0 op_sel_hi:[1,0]
	v_pk_mul_f32 v[86:87], v[14:15], v[18:19]
	v_pk_mul_f32 v[88:89], v[12:13], v[16:17]
	global_load_dwordx4 v[12:15], v[72:73], off offset:3072
	global_load_dwordx4 v[16:19], v126, s[10:11]
	global_load_dwordx4 v[20:23], v126, s[12:13]
	s_waitcnt vmcnt(1)
	v_pk_add_f32 v[18:19], v[18:19], 1.0 op_sel_hi:[1,0]
	v_pk_add_f32 v[16:17], v[16:17], 1.0 op_sel_hi:[1,0]
	v_pk_mul_f32 v[90:91], v[14:15], v[18:19]
	v_pk_mul_f32 v[92:93], v[12:13], v[16:17]
	global_load_dwordx4 v[12:15], v[70:71], off
	global_load_dwordx4 v[24:27], v120, s[10:11]
	global_load_dwordx4 v[16:19], v120, s[12:13]
	s_waitcnt vmcnt(1)
	v_pk_add_f32 v[26:27], v[26:27], 1.0 op_sel_hi:[1,0]
	v_pk_add_f32 v[24:25], v[24:25], 1.0 op_sel_hi:[1,0]
	v_pk_mul_f32 v[94:95], v[14:15], v[26:27]
	v_pk_mul_f32 v[96:97], v[12:13], v[24:25]
	global_load_dwordx4 v[12:15], v[68:69], off
	global_load_dwordx4 v[28:31], v121, s[10:11]
	global_load_dwordx4 v[24:27], v121, s[12:13]
	s_waitcnt vmcnt(1)
	v_pk_add_f32 v[30:31], v[30:31], 1.0 op_sel_hi:[1,0]
	v_pk_add_f32 v[28:29], v[28:29], 1.0 op_sel_hi:[1,0]
	v_pk_mul_f32 v[98:99], v[14:15], v[30:31]
	v_pk_mul_f32 v[100:101], v[12:13], v[28:29]
	global_load_dwordx4 v[12:15], v[66:67], off
	global_load_dwordx4 v[102:105], v122, s[10:11]
	global_load_dwordx4 v[28:31], v122, s[12:13]
	s_waitcnt vmcnt(1)
	v_pk_add_f32 v[104:105], v[104:105], 1.0 op_sel_hi:[1,0]
	v_pk_add_f32 v[106:107], v[102:103], 1.0 op_sel_hi:[1,0]
	v_pk_mul_f32 v[102:103], v[14:15], v[104:105]
	v_pk_mul_f32 v[104:105], v[12:13], v[106:107]
	global_load_dwordx4 v[108:111], v[64:65], off
	global_load_dwordx4 v[130:133], v123, s[10:11]
	global_load_dwordx4 v[12:15], v123, s[12:13]
	s_lshl_b64 s[10:11], s[4:5], 13
	s_add_u32 s12, s16, s10
	s_addc_u32 s13, s17, s11
	s_add_u32 s20, s12, 0x400000
	s_addc_u32 s21, s13, 0
	s_waitcnt vmcnt(1)
; template <bool GATES>
; __device__ __forceinline__ void norm_mod_phase(const Frame& F, const float* src0, const float* src1, const float* nw, int sh_off, int sc_off, int nparts, float* x1out) {
;     ...
;             if (nparts > 0) {
;                 for (int z = 0; z < nparts; ++z) { const f32x4* pp = (const f32x4*)(F.ws + WS_PART) + ((size_t)z * MS + (r - SP)) * (D / 4);
; #pragma unroll
;                     for (int i = 0; i < 8; ++i) xv[i] += pp[i * 64 + F.lane]; }
; #pragma unroll
;                 for (int i = 0; i < 8; ++i) ((f32x4*)(x1out + (size_t)(r - SP) * D))[i * 64 + F.lane] = xv[i]; } }
	v_pk_add_f32 v[106:107], v[132:133], 1.0 op_sel_hi:[1,0]
	v_pk_add_f32 v[112:113], v[130:131], 1.0 op_sel_hi:[1,0]
	v_pk_mul_f32 v[106:107], v[110:111], v[106:107]
	v_pk_mul_f32 v[108:109], v[108:109], v[112:113]
	global_load_dwordx4 v[168:171], v128, s[12:13]
	global_load_dwordx4 v[172:175], v128, s[12:13] offset:1024
	global_load_dwordx4 v[176:179], v128, s[12:13] offset:2048
	global_load_dwordx4 v[180:183], v128, s[12:13] offset:3072
	global_load_dwordx4 v[184:187], v120, s[12:13]
	global_load_dwordx4 v[188:191], v121, s[12:13]
	global_load_dwordx4 v[192:195], v122, s[12:13]
	global_load_dwordx4 v[196:199], v123, s[12:13]
	global_load_dwordx4 v[200:203], v128, s[20:21]
	global_load_dwordx4 v[204:207], v124, s[20:21]
	global_load_dwordx4 v[208:211], v125, s[20:21]
	global_load_dwordx4 v[212:215], v126, s[20:21]
	global_load_dwordx4 v[216:219], v120, s[20:21]
	global_load_dwordx4 v[220:223], v121, s[20:21]
	global_load_dwordx4 v[224:227], v122, s[20:21]
	global_load_dwordx4 v[228:231], v123, s[20:21]
	s_add_u32 s20, s12, 0x800000
	s_addc_u32 s21, s13, 0
	s_add_u32 s12, s12, 0xc00000
	s_addc_u32 s13, s13, 0
	s_waitcnt vmcnt(8)
	v_pk_add_f32 v[58:59], v[58:59], v[170:171]
	v_pk_add_f32 v[56:57], v[56:57], v[168:169]
	v_pk_add_f32 v[54:55], v[54:55], v[174:175]
	v_pk_add_f32 v[52:53], v[52:53], v[172:173]
	v_pk_add_f32 v[50:51], v[50:51], v[178:179]
	v_pk_add_f32 v[48:49], v[48:49], v[176:177]
	v_pk_add_f32 v[46:47], v[46:47], v[182:183]
	v_pk_add_f32 v[44:45], v[44:45], v[180:181]
	v_pk_add_f32 v[42:43], v[42:43], v[186:187]
	v_pk_add_f32 v[40:41], v[40:41], v[184:185]
	v_pk_add_f32 v[38:39], v[38:39], v[190:191]
	v_pk_add_f32 v[36:37], v[36:37], v[188:189]
	v_pk_add_f32 v[34:35], v[34:35], v[194:195]
	v_pk_add_f32 v[32:33], v[32:33], v[192:193]
	v_pk_add_f32 v[62:63], v[62:63], v[198:199]
	v_pk_add_f32 v[60:61], v[60:61], v[196:197]
	global_load_dwordx4 v[168:171], v128, s[20:21]
	global_load_dwordx4 v[172:175], v124, s[20:21]
	global_load_dwordx4 v[176:179], v125, s[20:21]
	global_load_dwordx4 v[180:183], v126, s[20:21]
	global_load_dwordx4 v[184:187], v120, s[20:21]
	global_load_dwordx4 v[188:191], v121, s[20:21]
	global_load_dwordx4 v[192:195], v122, s[20:21]
	global_load_dwordx4 v[196:199], v123, s[20:21]
	s_waitcnt vmcnt(8)
	v_pk_add_f32 v[58:59], v[58:59], v[202:203]
	v_pk_add_f32 v[56:57], v[56:57], v[200:201]
	v_pk_add_f32 v[54:55], v[54:55], v[206:207]
	v_pk_add_f32 v[52:53], v[52:53], v[204:205]
	v_pk_add_f32 v[50:51], v[50:51], v[210:211]
	v_pk_add_f32 v[48:49], v[48:49], v[208:209]
	v_pk_add_f32 v[46:47], v[46:47], v[214:215]
	v_pk_add_f32 v[44:45], v[44:45], v[212:213]
	v_pk_add_f32 v[42:43], v[42:43], v[218:219]
	v_pk_add_f32 v[40:41], v[40:41], v[216:217]
	v_pk_add_f32 v[38:39], v[38:39], v[222:223]
	v_pk_add_f32 v[36:37], v[36:37], v[220:221]
	v_pk_add_f32 v[34:35], v[34:35], v[226:227]
	v_pk_add_f32 v[32:33], v[32:33], v[224:225]
	v_pk_add_f32 v[62:63], v[62:63], v[230:231]
	v_pk_add_f32 v[60:61], v[60:61], v[228:229]
	global_load_dwordx4 v[200:203], v128, s[12:13]
	global_load_dwordx4 v[204:207], v124, s[12:13]
	global_load_dwordx4 v[208:211], v125, s[12:13]
	global_load_dwordx4 v[212:215], v126, s[12:13]
	global_load_dwordx4 v[216:219], v120, s[12:13]
	global_load_dwordx4 v[220:223], v121, s[12:13]
	global_load_dwordx4 v[224:227], v122, s[12:13]
	global_load_dwordx4 v[228:231], v123, s[12:13]
	s_waitcnt vmcnt(8)
	v_pk_add_f32 v[58:59], v[58:59], v[170:171]
	v_pk_add_f32 v[56:57], v[56:57], v[168:169]
	v_pk_add_f32 v[54:55], v[54:55], v[174:175]
	v_pk_add_f32 v[52:53], v[52:53], v[172:173]
	v_pk_add_f32 v[50:51], v[50:51], v[178:179]
	v_pk_add_f32 v[48:49], v[48:49], v[176:177]
	v_pk_add_f32 v[46:47], v[46:47], v[182:183]
	v_pk_add_f32 v[44:45], v[44:45], v[180:181]
	v_pk_add_f32 v[42:43], v[42:43], v[186:187]
	v_pk_add_f32 v[40:41], v[40:41], v[184:185]
	v_pk_add_f32 v[38:39], v[38:39], v[190:191]
	v_pk_add_f32 v[36:37], v[36:37], v[188:189]
	v_pk_add_f32 v[34:35], v[34:35], v[194:195]
	v_pk_add_f32 v[32:33], v[32:33], v[192:193]
	v_pk_add_f32 v[62:63], v[62:63], v[198:199]
	v_pk_add_f32 v[60:61], v[60:61], v[196:197]
	s_waitcnt vmcnt(0)
	v_pk_add_f32 v[58:59], v[58:59], v[202:203]
	v_pk_add_f32 v[56:57], v[56:57], v[200:201]
	v_pk_add_f32 v[54:55], v[54:55], v[206:207]
	v_pk_add_f32 v[52:53], v[52:53], v[204:205]
	v_pk_add_f32 v[50:51], v[50:51], v[210:211]
	v_pk_add_f32 v[48:49], v[48:49], v[208:209]
	v_pk_add_f32 v[46:47], v[46:47], v[214:215]
	v_pk_add_f32 v[44:45], v[44:45], v[212:213]
	v_pk_add_f32 v[42:43], v[42:43], v[218:219]
	v_pk_add_f32 v[40:41], v[40:41], v[216:217]
	v_pk_add_f32 v[38:39], v[38:39], v[222:223]
	v_pk_add_f32 v[36:37], v[36:37], v[220:221]
	v_pk_add_f32 v[34:35], v[34:35], v[226:227]
	v_pk_add_f32 v[32:33], v[32:33], v[224:225]
	v_pk_add_f32 v[62:63], v[62:63], v[230:231]
	v_pk_add_f32 v[60:61], v[60:61], v[228:229]
	v_lshl_add_u64 v[110:111], v[74:75], 0, s[10:11]
	global_store_dwordx4 v[110:111], v[56:59], off
	global_store_dwordx4 v[110:111], v[52:55], off offset:1024
	global_store_dwordx4 v[110:111], v[48:51], off offset:2048
	global_store_dwordx4 v[110:111], v[44:47], off offset:3072
	v_add_co_u32_e32 v110, vcc, s18, v110
	s_nop 1
	v_addc_co_u32_e32 v111, vcc, 0, v111, vcc
	global_store_dwordx4 v[110:111], v[40:43], off
	global_store_dwordx4 v[110:111], v[36:39], off offset:1024
	global_store_dwordx4 v[110:111], v[32:35], off offset:2048
	global_store_dwordx4 v[110:111], v[60:63], off offset:3072
	s_branch .LBB0_965

;     __device__ __forceinline__ void operator()(const f32x4 (&acc)[2][2][4][2], const Unit& u, int wr, int wc, int fr, int fq) const {
;     ...
;         if (tid < 256) { float tot = 0.f; const float* sp = ssq + (size_t)(u.pm * 8) * 256 + tid;
; #pragma unroll 1
;             for (int j = 0; j < 8; ++j) { tot += __hip_atomic_load(sp, __ATOMIC_RELAXED, __HIP_MEMORY_SCOPE_AGENT); sp += 256; }
;             red[1024 + tid] = rsqrtf(tot * (1.f / D) + EPS); }
.LBB0_1179:
	global_load_dword v200, v[128:129], off sc1
	global_load_dword v201, v[128:129], off offset:1024 sc1
	global_load_dword v202, v[128:129], off offset:2048 sc1
	global_load_dword v203, v[128:129], off offset:3072 sc1
	v_add_co_u32_e32 v208, vcc, 0x1000, v128
	s_nop 1
	v_addc_co_u32_e32 v209, vcc, 0, v129, vcc
	global_load_dword v204, v[208:209], off sc1
	global_load_dword v205, v[208:209], off offset:1024 sc1
	global_load_dword v206, v[208:209], off offset:2048 sc1
	global_load_dword v207, v[208:209], off offset:3072 sc1
	s_waitcnt vmcnt(7)
	v_add_f32_e32 v130, v130, v200
	s_waitcnt vmcnt(6)
	v_add_f32_e32 v130, v130, v201
	s_waitcnt vmcnt(5)
	v_add_f32_e32 v130, v130, v202
	s_waitcnt vmcnt(4)
	v_add_f32_e32 v130, v130, v203
	s_waitcnt vmcnt(3)
	v_add_f32_e32 v130, v130, v204
	s_waitcnt vmcnt(2)
	v_add_f32_e32 v130, v130, v205
	s_waitcnt vmcnt(1)
	v_add_f32_e32 v130, v130, v206
	s_waitcnt vmcnt(0)
	v_add_f32_e32 v130, v130, v207
	v_fmamk_f32 v128, v130, 0x3a000000, v186
	v_mul_f32_e32 v129, 0x4b800000, v128
	v_cmp_gt_f32_e32 vcc, s82, v128
	s_nop 1
	v_cndmask_b32_e32 v128, v128, v129, vcc
	v_rsq_f32_e32 v128, v128
	s_nop 0
	v_mul_f32_e32 v129, 0x45800000, v128
	v_cndmask_b32_e32 v128, v128, v129, vcc
	ds_write_b32 v187, v128 offset:4096
